# ffwide: forget-gate tile epilogue spread over all 512 threads via 8KiB LDS exchange + 1 barrier (replaces 2-wave 1254-instr epilogue)
# baseline (speedup 1.0000x reference)
; __device__ __forceinline__ float logsig_f(float x) { return fminf(x, 0.f) - __logf(1.f + __expf(-fabsf(x))); }
;     __device__ __forceinline__ void operator()(const f32x4 (&acc)[2][2][4][2], const pg8::Unit& u, int wr, int wc, int fr, int fq) const {
;     ...
;         if (pn == 14) {
;             if (wc == 0 && fq == 0) {
;                 const f32x4 fb0 = *(const f32x4*)fbias, fb1 = *(const f32x4*)(fbias + 4);
; #pragma unroll
;                 for (int ai = 0; ai < 2; ++ai)
; #pragma unroll
;                     for (int m = 0; m < 4; ++m) {
;                         const int row = row0 + ai * 128 + m * 16;
;                         const f32x4 sv = *(const f32x4*)(ssq + (size_t)row * 16), sv1 = *(const f32x4*)(ssq + (size_t)row * 16 + 4), sv2 = *(const f32x4*)(ssq + (size_t)row * 16 + 8), sv3 = *(const f32x4*)(ssq + (size_t)row * 16 + 12);
;                         const float st = ((sv[0] + sv[1]) + (sv[2] + sv[3])) + ((sv1[0] + sv1[1]) + (sv1[2] + sv1[3])) + ((sv2[0] + sv2[1]) + (sv2[2] + sv2[3])) + ((sv3[0] + sv3[1]) + (sv3[2] + sv3[3]));
;                         const float rs = __builtin_amdgcn_rsqf(st * (1.f / DM) + EPS);
;                         f32x4 a = acc[ai][0][m][0] * rs, b = acc[ai][0][m][1] * rs;
; #pragma unroll
;                         for (int i = 0; i < 4; ++i) { a[i] = logsig_f(a[i] + fb0[i]) * LOG2E; b[i] = logsig_f(b[i] + fb1[i]) * LOG2E; }
;                         *(f32x4*)(FF + (size_t)row * 8) = a; *(f32x4*)(FF + (size_t)row * 8 + 4) = b;
;                         asm volatile("" ::: "memory");
.LBB0_420:
	v_sub_u32_e32 v128, v166, v172
	v_lshrrev_b32_e32 v129, 1, v203
	v_and_b32_e32 v130, 1, v203
	v_add_u32_e32 v128, v128, v129
	v_lshlrev_b32_e32 v131, 4, v130
	v_lshlrev_b32_e32 v132, 6, v128
	global_load_dwordx4 v[136:139], v132, s[82:83]
	global_load_dwordx4 v[140:143], v132, s[82:83] offset:16
	global_load_dwordx4 v[144:147], v132, s[82:83] offset:32
	global_load_dwordx4 v[148:151], v132, s[82:83] offset:48
	global_load_dwordx4 v[176:179], v131, s[34:35]
	s_add_i32 s8, s69, 0x20000
	s_mov_b32 s2, 0x3fb8aa3b
	v_lshlrev_b32_e32 v133, 5, v172
	v_lshlrev_b32_e32 v134, 4, v203
	v_add_u32_e32 v133, s8, v133
	v_add_u32_e32 v134, s8, v134
	s_and_saveexec_b64 s[10:11], s[38:39]
	ds_write_b128 v133, v[60:63]
	ds_write_b128 v133, v[56:59] offset:16
	ds_write_b128 v133, v[52:55] offset:512
	ds_write_b128 v133, v[48:51] offset:528
	ds_write_b128 v133, v[44:47] offset:1024
	ds_write_b128 v133, v[40:43] offset:1040
	ds_write_b128 v133, v[36:39] offset:1536
	ds_write_b128 v133, v[32:35] offset:1552
	ds_write_b128 v133, v[28:31] offset:4096
	ds_write_b128 v133, v[24:27] offset:4112
	ds_write_b128 v133, v[20:23] offset:4608
	ds_write_b128 v133, v[16:19] offset:4624
	ds_write_b128 v133, v[12:15] offset:5120
	ds_write_b128 v133, v[8:11] offset:5136
	ds_write_b128 v133, v[4:7] offset:5632
	ds_write_b128 v133, v[0:3] offset:5648
	s_or_b64 exec, exec, s[10:11]
	s_waitcnt lgkmcnt(0)
	s_barrier
	ds_read_b128 v[180:183], v134
	s_waitcnt vmcnt(0) lgkmcnt(0)
	v_add_f32_e32 v136, v136, v137
	v_add_f32_e32 v138, v138, v139
	v_add_f32_e32 v140, v140, v141
	v_add_f32_e32 v142, v142, v143
	v_add_f32_e32 v144, v144, v145
	v_add_f32_e32 v146, v146, v147
	v_add_f32_e32 v148, v148, v149
	v_add_f32_e32 v150, v150, v151
	v_add_f32_e32 v136, v136, v138
	v_add_f32_e32 v140, v140, v142
	v_add_f32_e32 v144, v144, v146
	v_add_f32_e32 v148, v148, v150
	v_add_f32_e32 v136, v136, v140
	v_add_f32_e32 v136, v136, v144
	v_add_f32_e32 v136, v136, v148
	v_fmamk_f32 v136, v136, 0x3a800000, v212
	v_rsq_f32_e32 v136, v136
	s_nop 0
	v_mul_f32_e32 v180, v180, v136
	v_mul_f32_e32 v181, v181, v136
	v_mul_f32_e32 v182, v182, v136
	v_mul_f32_e32 v183, v183, v136
	v_add_f32_e32 v180, v176, v180
	v_add_f32_e32 v181, v177, v181
	v_add_f32_e32 v182, v178, v182
	v_add_f32_e32 v183, v179, v183
	v_min_f32_e32 v184, 0, v180
	v_min_f32_e32 v185, 0, v181
	v_min_f32_e32 v186, 0, v182
	v_min_f32_e32 v187, 0, v183
	v_mul_f32_e64 v188, |v180|, s57
	v_mul_f32_e64 v189, |v181|, s57
	v_mul_f32_e64 v190, |v182|, s57
	v_mul_f32_e64 v191, |v183|, s57
	v_exp_f32_e32 v188, v188
	v_exp_f32_e32 v189, v189
	v_exp_f32_e32 v190, v190
	v_exp_f32_e32 v191, v191
	v_add_f32_e32 v188, 1.0, v188
	v_add_f32_e32 v189, 1.0, v189
	v_add_f32_e32 v190, 1.0, v190
	v_add_f32_e32 v191, 1.0, v191
	v_log_f32_e32 v188, v188
	v_log_f32_e32 v189, v189
	v_log_f32_e32 v190, v190
	v_log_f32_e32 v191, v191
	v_mul_f32_e32 v144, 0x3f317217, v188
	v_mul_f32_e32 v145, 0x3f317217, v189
	v_mul_f32_e32 v146, 0x3f317217, v190
	v_mul_f32_e32 v147, 0x3f317217, v191
	v_fma_f32 v144, v188, s52, -v144
	v_fma_f32 v145, v189, s52, -v145
	v_fma_f32 v146, v190, s52, -v146
	v_fma_f32 v147, v191, s52, -v147
	v_fmac_f32_e32 v144, 0x3377d1cf, v188
	v_fmac_f32_e32 v145, 0x3377d1cf, v189
	v_fmac_f32_e32 v146, 0x3377d1cf, v190
	v_fmac_f32_e32 v147, 0x3377d1cf, v191
	v_fmac_f32_e32 v144, 0x3f317217, v188
	v_fmac_f32_e32 v145, 0x3f317217, v189
	v_fmac_f32_e32 v146, 0x3f317217, v190
	v_fmac_f32_e32 v147, 0x3f317217, v191
	v_sub_f32_e32 v148, v184, v144
	v_sub_f32_e32 v149, v185, v145
	v_sub_f32_e32 v150, v186, v146
	v_sub_f32_e32 v151, v187, v147
	v_mul_f32_e32 v148, s2, v148
	v_mul_f32_e32 v149, s2, v149
	v_mul_f32_e32 v150, s2, v150
	v_mul_f32_e32 v151, s2, v151
	v_lshlrev_b32_e32 v135, 5, v128
	v_add_u32_e32 v135, v135, v131
	global_store_dwordx4 v135, v[148:151], s[42:43]
